# in-proj epilogue rope sections: second rope row requested at the top of the section (overlaps the first row's load round trip), staged in the zero high halves of the K-loop staging offsets
# baseline (speedup 1.0000x reference)
;   DEVI f32x4 xform(int m, int n, f32x4 v, float rs) const {
;     ...
;     if (ri >= 0) {
;       const float4 cs = *(const float4*)(rope + ((size_t)m * 56 + ri) * 2);
;       float a0 = v[0] * cs.x - v[1] * cs.y, a1 = v[1] * cs.x + v[0] * cs.y;
;       float a2 = v[2] * cs.z - v[3] * cs.w, a3 = v[3] * cs.z + v[2] * cs.w;
;       v = (f32x4){a0, a1, a2, a3};
;     }
;   DEVI void operator()(const f32x4 (&acc)[2][2][4][2], const pg8::Unit& u, int wr, int wc, int fr, int fq) const {
;     ...
;           const f32x4 a0 = ai ? acc[1][bj][m][0] : acc[0][bj][m][0], a1 = ai ? acc[1][bj][m][1] : acc[0][bj][m][1];
;           if (u.pn < 9) {
;             const f32x4 v0 = xform(row, col, a0, rs), v1 = xform(row, col + 4, a1, rs);
.LBB0_487:
	v_mov_b32_e32 v207, v206
	v_mad_i64_i32 v[210:211], s[38:39], v204, 56, 0
	s_andn2_b64 vcc, exec, s[34:35]
	v_mad_i64_i32 v[208:209], s[34:35], v204, s33, 0
	s_cbranch_vccnz .LBB0_493
	v_mov_b32_e32 v222, v206
	v_mov_b32_e32 v223, v206
	v_pk_mul_f32 v[220:221], v[216:217], v[222:223]
	v_pk_mul_f32 v[216:217], v[218:219], v[206:207]
	s_and_saveexec_b64 s[34:35], s[30:31]
	v_readlane_b32 s38, v252, 63
	v_readlane_b32 s39, v253, 0
	v_add_u32_e32 v147, v210, v200
	v_lshlrev_b32_e32 v147, 3, v147
	s_nop 3
	global_load_dword v137, v147, s[38:39]
	global_load_dword v139, v147, s[38:39] offset:4
	global_load_dword v141, v147, s[38:39] offset:8
	global_load_dword v143, v147, s[38:39] offset:12
	s_or_b64 exec, exec, s[34:35]
	s_and_saveexec_b64 s[34:35], s[28:29]
	s_cbranch_execz .LBB0_490
	v_readlane_b32 s38, v252, 63
	v_lshl_add_u64 v[132:133], v[210:211], 0, v[194:195]
	v_readlane_b32 s39, v253, 0
	s_nop 1
	v_lshl_add_u64 v[132:133], v[132:133], 3, s[38:39]
	global_load_dwordx4 v[132:135], v[132:133], off
	s_waitcnt vmcnt(0)
	v_pk_mul_f32 v[228:229], v[216:217], v[132:133] op_sel:[1,1] op_sel_hi:[0,1]
	v_mul_f32_e32 v32, v221, v135
	v_pk_mul_f32 v[218:219], v[216:217], v[132:133] op_sel_hi:[1,0]
	v_pk_fma_f32 v[216:217], v[216:217], v[132:133], v[228:229] op_sel_hi:[1,0,1]
	v_pk_fma_f32 v[132:133], v[220:221], v[134:135], v[32:33] op_sel_hi:[1,1,0] neg_lo:[0,0,1] neg_hi:[0,0,1]
	v_mul_f32_e32 v32, v220, v135
	v_pk_fma_f32 v[134:135], v[220:221], v[134:135], v[32:33] op_sel:[1,0,0] op_sel_hi:[0,1,0]
	v_sub_f32_e32 v216, v218, v228
	v_mov_b32_e32 v220, v132
	v_mov_b32_e32 v221, v134
.LBB0_490:
	s_or_b64 exec, exec, s[34:35]
	v_pk_mul_f32 v[218:219], v[212:213], v[222:223]
	v_pk_mul_f32 v[212:213], v[214:215], v[206:207]
	s_and_saveexec_b64 s[34:35], s[30:31]
	s_cbranch_execz .LBB0_492
	s_waitcnt vmcnt(0)
	v_mov_b32_e32 v132, v137
	v_mov_b32_e32 v133, v139
	v_mov_b32_e32 v134, v141
	v_mov_b32_e32 v135, v143
	v_mov_b32_e32 v137, 0
	v_mov_b32_e32 v139, 0
	v_mov_b32_e32 v141, 0
	v_mov_b32_e32 v143, 0
	v_mov_b32_e32 v147, 0
	v_pk_mul_f32 v[222:223], v[212:213], v[132:133] op_sel:[1,1] op_sel_hi:[0,1]
	v_mul_f32_e32 v32, v219, v135
	v_pk_mul_f32 v[214:215], v[212:213], v[132:133] op_sel_hi:[1,0]
	v_pk_fma_f32 v[212:213], v[212:213], v[132:133], v[222:223] op_sel_hi:[1,0,1]
	v_pk_fma_f32 v[132:133], v[218:219], v[134:135], v[32:33] op_sel_hi:[1,1,0] neg_lo:[0,0,1] neg_hi:[0,0,1]
	v_mul_f32_e32 v32, v218, v135
	v_pk_fma_f32 v[134:135], v[218:219], v[134:135], v[32:33] op_sel:[1,0,0] op_sel_hi:[0,1,0]
	v_sub_f32_e32 v212, v214, v222
	v_mov_b32_e32 v218, v132
	v_mov_b32_e32 v219, v134

;   DEVI f32x4 xform(int m, int n, f32x4 v, float rs) const {
;     ...
;     if (ri >= 0) {
;       const float4 cs = *(const float4*)(rope + ((size_t)m * 56 + ri) * 2);
;       float a0 = v[0] * cs.x - v[1] * cs.y, a1 = v[1] * cs.x + v[0] * cs.y;
;       float a2 = v[2] * cs.z - v[3] * cs.w, a3 = v[3] * cs.z + v[2] * cs.w;
;       v = (f32x4){a0, a1, a2, a3};
;     }
;   DEVI void operator()(const f32x4 (&acc)[2][2][4][2], const pg8::Unit& u, int wr, int wc, int fr, int fq) const {
;     ...
;           const f32x4 a0 = ai ? acc[1][bj][m][0] : acc[0][bj][m][0], a1 = ai ? acc[1][bj][m][1] : acc[0][bj][m][1];
;           if (u.pn < 9) {
;             const f32x4 v0 = xform(row, col, a0, rs), v1 = xform(row, col + 4, a1, rs);
.LBB0_504:
	s_andn2_b64 vcc, exec, s[38:39]
	s_cbranch_vccnz .LBB0_510
	v_mov_b32_e32 v222, v206
	v_mov_b32_e32 v223, v206
	v_pk_mul_f32 v[220:221], v[216:217], v[222:223]
	v_pk_mul_f32 v[216:217], v[218:219], v[206:207]
	s_and_saveexec_b64 s[38:39], s[18:19]
	v_readlane_b32 s40, v252, 63
	v_readlane_b32 s41, v253, 0
	v_add_u32_e32 v147, v210, v158
	v_lshlrev_b32_e32 v147, 3, v147
	s_nop 3
	global_load_dword v137, v147, s[40:41]
	global_load_dword v139, v147, s[40:41] offset:4
	global_load_dword v141, v147, s[40:41] offset:8
	global_load_dword v143, v147, s[40:41] offset:12
	s_or_b64 exec, exec, s[38:39]
	s_and_saveexec_b64 s[38:39], s[16:17]
	s_cbranch_execz .LBB0_507
	v_readlane_b32 s40, v252, 63
	v_lshl_add_u64 v[132:133], v[210:211], 0, v[152:153]
	v_readlane_b32 s41, v253, 0
	s_nop 1
	v_lshl_add_u64 v[132:133], v[132:133], 3, s[40:41]
	global_load_dwordx4 v[132:135], v[132:133], off
	s_waitcnt vmcnt(0)
	v_pk_mul_f32 v[228:229], v[216:217], v[132:133] op_sel:[1,1] op_sel_hi:[0,1]
	v_mul_f32_e32 v32, v221, v135
	v_pk_mul_f32 v[218:219], v[216:217], v[132:133] op_sel_hi:[1,0]
	v_pk_fma_f32 v[216:217], v[216:217], v[132:133], v[228:229] op_sel_hi:[1,0,1]
	v_pk_fma_f32 v[132:133], v[220:221], v[134:135], v[32:33] op_sel_hi:[1,1,0] neg_lo:[0,0,1] neg_hi:[0,0,1]
	v_mul_f32_e32 v32, v220, v135
	v_pk_fma_f32 v[134:135], v[220:221], v[134:135], v[32:33] op_sel:[1,0,0] op_sel_hi:[0,1,0]
	v_sub_f32_e32 v216, v218, v228
	v_mov_b32_e32 v220, v132
	v_mov_b32_e32 v221, v134
.LBB0_507:
	s_or_b64 exec, exec, s[38:39]
	v_pk_mul_f32 v[212:213], v[212:213], v[222:223]
	v_pk_mul_f32 v[206:207], v[214:215], v[206:207]
	s_and_saveexec_b64 s[38:39], s[18:19]
	s_cbranch_execz .LBB0_509
	s_waitcnt vmcnt(0)
	v_mov_b32_e32 v132, v137
	v_mov_b32_e32 v133, v139
	v_mov_b32_e32 v134, v141
	v_mov_b32_e32 v135, v143
	v_mov_b32_e32 v137, 0
	v_mov_b32_e32 v139, 0
	v_mov_b32_e32 v141, 0
	v_mov_b32_e32 v143, 0
	v_mov_b32_e32 v147, 0
	v_pk_mul_f32 v[214:215], v[206:207], v[132:133] op_sel:[1,1] op_sel_hi:[0,1]
	v_mul_f32_e32 v32, v213, v135
	v_pk_mul_f32 v[210:211], v[206:207], v[132:133] op_sel_hi:[1,0]
	v_pk_fma_f32 v[206:207], v[206:207], v[132:133], v[214:215] op_sel_hi:[1,0,1]
	v_pk_fma_f32 v[132:133], v[212:213], v[134:135], v[32:33] op_sel_hi:[1,1,0] neg_lo:[0,0,1] neg_hi:[0,0,1]
	v_mul_f32_e32 v32, v212, v135
	v_pk_fma_f32 v[134:135], v[212:213], v[134:135], v[32:33] op_sel:[1,0,0] op_sel_hi:[0,1,0]
	v_sub_f32_e32 v206, v210, v214
	v_mov_b32_e32 v212, v132
	v_mov_b32_e32 v213, v134

;   DEVI f32x4 xform(int m, int n, f32x4 v, float rs) const {
;     ...
;     if (ri >= 0) {
;       const float4 cs = *(const float4*)(rope + ((size_t)m * 56 + ri) * 2);
;       float a0 = v[0] * cs.x - v[1] * cs.y, a1 = v[1] * cs.x + v[0] * cs.y;
;       float a2 = v[2] * cs.z - v[3] * cs.w, a3 = v[3] * cs.z + v[2] * cs.w;
;       v = (f32x4){a0, a1, a2, a3};
;     }
;   DEVI void operator()(const f32x4 (&acc)[2][2][4][2], const pg8::Unit& u, int wr, int wc, int fr, int fq) const {
;     ...
;           const f32x4 a0 = ai ? acc[1][bj][m][0] : acc[0][bj][m][0], a1 = ai ? acc[1][bj][m][1] : acc[0][bj][m][1];
;           if (u.pn < 9) {
;             const f32x4 v0 = xform(row, col, a0, rs), v1 = xform(row, col + 4, a1, rs);
.LBB0_521:
	v_mov_b32_e32 v207, v206
	v_mad_i64_i32 v[210:211], s[40:41], v208, 56, 0
	s_andn2_b64 vcc, exec, s[38:39]
	v_mad_i64_i32 v[208:209], s[38:39], v208, s33, 0
	s_cbranch_vccnz .LBB0_527
	v_mov_b32_e32 v222, v206
	v_mov_b32_e32 v223, v206
	v_pk_mul_f32 v[220:221], v[214:215], v[222:223]
	v_pk_mul_f32 v[214:215], v[216:217], v[206:207]
	s_and_saveexec_b64 s[38:39], s[22:23]
	v_readlane_b32 s40, v252, 63
	v_readlane_b32 s41, v253, 0
	v_add_u32_e32 v147, v210, v170
	v_lshlrev_b32_e32 v147, 3, v147
	s_nop 3
	global_load_dword v137, v147, s[40:41]
	global_load_dword v139, v147, s[40:41] offset:4
	global_load_dword v141, v147, s[40:41] offset:8
	global_load_dword v143, v147, s[40:41] offset:12
	s_or_b64 exec, exec, s[38:39]
	s_and_saveexec_b64 s[38:39], s[20:21]
	s_cbranch_execz .LBB0_524
	v_readlane_b32 s40, v252, 63
	v_lshl_add_u64 v[132:133], v[210:211], 0, v[164:165]
	v_readlane_b32 s41, v253, 0
	s_nop 1
	v_lshl_add_u64 v[132:133], v[132:133], 3, s[40:41]
	global_load_dwordx4 v[132:135], v[132:133], off
	s_waitcnt vmcnt(0)
	v_pk_mul_f32 v[228:229], v[214:215], v[132:133] op_sel:[1,1] op_sel_hi:[0,1]
	v_mul_f32_e32 v32, v221, v135
	v_pk_mul_f32 v[216:217], v[214:215], v[132:133] op_sel_hi:[1,0]
	v_pk_fma_f32 v[214:215], v[214:215], v[132:133], v[228:229] op_sel_hi:[1,0,1]
	v_pk_fma_f32 v[132:133], v[220:221], v[134:135], v[32:33] op_sel_hi:[1,1,0] neg_lo:[0,0,1] neg_hi:[0,0,1]
	v_mul_f32_e32 v32, v220, v135
	v_pk_fma_f32 v[134:135], v[220:221], v[134:135], v[32:33] op_sel:[1,0,0] op_sel_hi:[0,1,0]
	v_sub_f32_e32 v214, v216, v228
	v_mov_b32_e32 v220, v132
	v_mov_b32_e32 v221, v134
.LBB0_524:
	s_or_b64 exec, exec, s[38:39]
	v_pk_mul_f32 v[216:217], v[212:213], v[222:223]
	v_pk_mul_f32 v[212:213], v[218:219], v[206:207]
	s_and_saveexec_b64 s[38:39], s[22:23]
	s_cbranch_execz .LBB0_526
	s_waitcnt vmcnt(0)
	v_mov_b32_e32 v132, v137
	v_mov_b32_e32 v133, v139
	v_mov_b32_e32 v134, v141
	v_mov_b32_e32 v135, v143
	v_mov_b32_e32 v137, 0
	v_mov_b32_e32 v139, 0
	v_mov_b32_e32 v141, 0
	v_mov_b32_e32 v143, 0
	v_mov_b32_e32 v147, 0
	v_pk_mul_f32 v[222:223], v[212:213], v[132:133] op_sel:[1,1] op_sel_hi:[0,1]
	v_mul_f32_e32 v32, v217, v135
	v_pk_mul_f32 v[218:219], v[212:213], v[132:133] op_sel_hi:[1,0]
	v_pk_fma_f32 v[212:213], v[212:213], v[132:133], v[222:223] op_sel_hi:[1,0,1]
	v_pk_fma_f32 v[132:133], v[216:217], v[134:135], v[32:33] op_sel_hi:[1,1,0] neg_lo:[0,0,1] neg_hi:[0,0,1]
	v_mul_f32_e32 v32, v216, v135
	v_pk_fma_f32 v[134:135], v[216:217], v[134:135], v[32:33] op_sel:[1,0,0] op_sel_hi:[0,1,0]
	v_sub_f32_e32 v212, v218, v222
	v_mov_b32_e32 v216, v132
	v_mov_b32_e32 v217, v134

;   DEVI f32x4 xform(int m, int n, f32x4 v, float rs) const {
;     ...
;     if (ri >= 0) {
;       const float4 cs = *(const float4*)(rope + ((size_t)m * 56 + ri) * 2);
;       float a0 = v[0] * cs.x - v[1] * cs.y, a1 = v[1] * cs.x + v[0] * cs.y;
;       float a2 = v[2] * cs.z - v[3] * cs.w, a3 = v[3] * cs.z + v[2] * cs.w;
;       v = (f32x4){a0, a1, a2, a3};
;     }
;   DEVI void operator()(const f32x4 (&acc)[2][2][4][2], const pg8::Unit& u, int wr, int wc, int fr, int fq) const {
;     ...
;           const f32x4 a0 = ai ? acc[1][bj][m][0] : acc[0][bj][m][0], a1 = ai ? acc[1][bj][m][1] : acc[0][bj][m][1];
;           if (u.pn < 9) {
;             const f32x4 v0 = xform(row, col, a0, rs), v1 = xform(row, col + 4, a1, rs);
.LBB0_538:
	s_andn2_b64 vcc, exec, s[38:39]
	s_cbranch_vccnz .LBB0_544
	v_mov_b32_e32 v222, v206
	v_mov_b32_e32 v223, v206
	v_pk_mul_f32 v[220:221], v[216:217], v[222:223]
	v_pk_mul_f32 v[216:217], v[218:219], v[206:207]
	s_and_saveexec_b64 s[38:39], s[26:27]
	v_readlane_b32 s40, v252, 63
	v_readlane_b32 s41, v253, 0
	v_add_u32_e32 v147, v210, v182
	v_lshlrev_b32_e32 v147, 3, v147
	s_nop 3
	global_load_dword v137, v147, s[40:41]
	global_load_dword v139, v147, s[40:41] offset:4
	global_load_dword v141, v147, s[40:41] offset:8
	global_load_dword v143, v147, s[40:41] offset:12
	s_or_b64 exec, exec, s[38:39]
	s_and_saveexec_b64 s[38:39], s[24:25]
	s_cbranch_execz .LBB0_541
	v_readlane_b32 s40, v252, 63
	v_lshl_add_u64 v[132:133], v[210:211], 0, v[176:177]
	v_readlane_b32 s41, v253, 0
	s_nop 1
	v_lshl_add_u64 v[132:133], v[132:133], 3, s[40:41]
	global_load_dwordx4 v[132:135], v[132:133], off
	s_waitcnt vmcnt(0)
	v_pk_mul_f32 v[228:229], v[216:217], v[132:133] op_sel:[1,1] op_sel_hi:[0,1]
	v_mul_f32_e32 v32, v221, v135
	v_pk_mul_f32 v[218:219], v[216:217], v[132:133] op_sel_hi:[1,0]
	v_pk_fma_f32 v[216:217], v[216:217], v[132:133], v[228:229] op_sel_hi:[1,0,1]
	v_pk_fma_f32 v[132:133], v[220:221], v[134:135], v[32:33] op_sel_hi:[1,1,0] neg_lo:[0,0,1] neg_hi:[0,0,1]
	v_mul_f32_e32 v32, v220, v135
	v_pk_fma_f32 v[134:135], v[220:221], v[134:135], v[32:33] op_sel:[1,0,0] op_sel_hi:[0,1,0]
	v_sub_f32_e32 v216, v218, v228
	v_mov_b32_e32 v220, v132
	v_mov_b32_e32 v221, v134
.LBB0_541:
	s_or_b64 exec, exec, s[38:39]
	v_pk_mul_f32 v[212:213], v[212:213], v[222:223]
	v_pk_mul_f32 v[206:207], v[214:215], v[206:207]
	s_and_saveexec_b64 s[38:39], s[26:27]
	s_cbranch_execz .LBB0_543
	s_waitcnt vmcnt(0)
	v_mov_b32_e32 v132, v137
	v_mov_b32_e32 v133, v139
	v_mov_b32_e32 v134, v141
	v_mov_b32_e32 v135, v143
	v_mov_b32_e32 v137, 0
	v_mov_b32_e32 v139, 0
	v_mov_b32_e32 v141, 0
	v_mov_b32_e32 v143, 0
	v_mov_b32_e32 v147, 0
	v_pk_mul_f32 v[214:215], v[206:207], v[132:133] op_sel:[1,1] op_sel_hi:[0,1]
	v_mul_f32_e32 v32, v213, v135
	v_pk_mul_f32 v[210:211], v[206:207], v[132:133] op_sel_hi:[1,0]
	v_pk_fma_f32 v[206:207], v[206:207], v[132:133], v[214:215] op_sel_hi:[1,0,1]
	v_pk_fma_f32 v[132:133], v[212:213], v[134:135], v[32:33] op_sel_hi:[1,1,0] neg_lo:[0,0,1] neg_hi:[0,0,1]
	v_mul_f32_e32 v32, v212, v135
	v_pk_fma_f32 v[134:135], v[212:213], v[134:135], v[32:33] op_sel:[1,0,0] op_sel_hi:[0,1,0]
	v_sub_f32_e32 v206, v210, v214
	v_mov_b32_e32 v212, v132
	v_mov_b32_e32 v213, v134

;   DEVI f32x4 xform(int m, int n, f32x4 v, float rs) const {
;     ...
;     if (ri >= 0) {
;       const float4 cs = *(const float4*)(rope + ((size_t)m * 56 + ri) * 2);
;       float a0 = v[0] * cs.x - v[1] * cs.y, a1 = v[1] * cs.x + v[0] * cs.y;
;       float a2 = v[2] * cs.z - v[3] * cs.w, a3 = v[3] * cs.z + v[2] * cs.w;
;       v = (f32x4){a0, a1, a2, a3};
;     }
;   DEVI void operator()(const f32x4 (&acc)[2][2][4][2], const pg8::Unit& u, int wr, int wc, int fr, int fq) const {
;     ...
;           const f32x4 a0 = ai ? acc[1][bj][m][0] : acc[0][bj][m][0], a1 = ai ? acc[1][bj][m][1] : acc[0][bj][m][1];
;           if (u.pn < 9) {
;             const f32x4 v0 = xform(row, col, a0, rs), v1 = xform(row, col + 4, a1, rs);
.LBB0_589:
	v_mov_b32_e32 v207, v206
	v_mad_i64_i32 v[210:211], s[40:41], v208, 56, 0
	s_andn2_b64 vcc, exec, s[38:39]
	v_mad_i64_i32 v[204:205], s[38:39], v208, s33, 0
	s_cbranch_vccnz .LBB0_595
	v_mov_b32_e32 v220, v206
	v_mov_b32_e32 v221, v206
	v_pk_mul_f32 v[214:215], v[214:215], v[220:221]
	v_pk_mul_f32 v[208:209], v[216:217], v[206:207]
	s_and_saveexec_b64 s[38:39], s[22:23]
	v_readlane_b32 s40, v252, 63
	v_readlane_b32 s41, v253, 0
	v_add_u32_e32 v147, v210, v170
	v_lshlrev_b32_e32 v147, 3, v147
	s_nop 3
	global_load_dword v137, v147, s[40:41]
	global_load_dword v139, v147, s[40:41] offset:4
	global_load_dword v141, v147, s[40:41] offset:8
	global_load_dword v143, v147, s[40:41] offset:12
	s_or_b64 exec, exec, s[38:39]
	s_and_saveexec_b64 s[38:39], s[20:21]
	s_cbranch_execz .LBB0_592
	v_readlane_b32 s40, v252, 63
	v_lshl_add_u64 v[132:133], v[210:211], 0, v[164:165]
	v_readlane_b32 s41, v253, 0
	s_nop 1
	v_lshl_add_u64 v[132:133], v[132:133], 3, s[40:41]
	global_load_dwordx4 v[132:135], v[132:133], off
	s_waitcnt vmcnt(0)
	v_pk_mul_f32 v[228:229], v[208:209], v[132:133] op_sel:[1,1] op_sel_hi:[0,1]
	v_mul_f32_e32 v32, v215, v135
	v_pk_mul_f32 v[216:217], v[208:209], v[132:133] op_sel_hi:[1,0]
	v_pk_fma_f32 v[208:209], v[208:209], v[132:133], v[228:229] op_sel_hi:[1,0,1]
	v_pk_fma_f32 v[132:133], v[214:215], v[134:135], v[32:33] op_sel_hi:[1,1,0] neg_lo:[0,0,1] neg_hi:[0,0,1]
	v_mul_f32_e32 v32, v214, v135
	v_pk_fma_f32 v[134:135], v[214:215], v[134:135], v[32:33] op_sel:[1,0,0] op_sel_hi:[0,1,0]
	v_sub_f32_e32 v208, v216, v228
	v_mov_b32_e32 v214, v132
	v_mov_b32_e32 v215, v134
.LBB0_592:
	s_or_b64 exec, exec, s[38:39]
	v_pk_mul_f32 v[216:217], v[212:213], v[220:221]
	v_pk_mul_f32 v[212:213], v[218:219], v[206:207]
	s_and_saveexec_b64 s[38:39], s[22:23]
	s_cbranch_execz .LBB0_594
	s_waitcnt vmcnt(0)
	v_mov_b32_e32 v132, v137
	v_mov_b32_e32 v133, v139
	v_mov_b32_e32 v134, v141
	v_mov_b32_e32 v135, v143
	v_mov_b32_e32 v137, 0
	v_mov_b32_e32 v139, 0
	v_mov_b32_e32 v141, 0
	v_mov_b32_e32 v143, 0
	v_mov_b32_e32 v147, 0
	v_pk_mul_f32 v[220:221], v[212:213], v[132:133] op_sel:[1,1] op_sel_hi:[0,1]
	v_mul_f32_e32 v32, v217, v135
	v_pk_mul_f32 v[218:219], v[212:213], v[132:133] op_sel_hi:[1,0]
	v_pk_fma_f32 v[212:213], v[212:213], v[132:133], v[220:221] op_sel_hi:[1,0,1]
	v_pk_fma_f32 v[132:133], v[216:217], v[134:135], v[32:33] op_sel_hi:[1,1,0] neg_lo:[0,0,1] neg_hi:[0,0,1]
	v_mul_f32_e32 v32, v216, v135
	v_pk_fma_f32 v[134:135], v[216:217], v[134:135], v[32:33] op_sel:[1,0,0] op_sel_hi:[0,1,0]
	v_sub_f32_e32 v212, v218, v220
	v_mov_b32_e32 v216, v132
	v_mov_b32_e32 v217, v134

;   DEVI f32x4 xform(int m, int n, f32x4 v, float rs) const {
;     ...
;     if (ri >= 0) {
;       const float4 cs = *(const float4*)(rope + ((size_t)m * 56 + ri) * 2);
;       float a0 = v[0] * cs.x - v[1] * cs.y, a1 = v[1] * cs.x + v[0] * cs.y;
;       float a2 = v[2] * cs.z - v[3] * cs.w, a3 = v[3] * cs.z + v[2] * cs.w;
;       v = (f32x4){a0, a1, a2, a3};
;     }
;   DEVI void operator()(const f32x4 (&acc)[2][2][4][2], const pg8::Unit& u, int wr, int wc, int fr, int fq) const {
;     ...
;           const f32x4 a0 = ai ? acc[1][bj][m][0] : acc[0][bj][m][0], a1 = ai ? acc[1][bj][m][1] : acc[0][bj][m][1];
;           if (u.pn < 9) {
;             const f32x4 v0 = xform(row, col, a0, rs), v1 = xform(row, col + 4, a1, rs);
.LBB0_606:
	s_andn2_b64 vcc, exec, s[34:35]
	s_cbranch_vccnz .LBB0_475
	v_mov_b32_e32 v220, v206
	v_mov_b32_e32 v221, v206
	v_pk_mul_f32 v[218:219], v[214:215], v[220:221]
	v_pk_mul_f32 v[214:215], v[216:217], v[206:207]
	s_and_saveexec_b64 s[34:35], s[26:27]
	v_readlane_b32 s38, v252, 63
	v_readlane_b32 s39, v253, 0
	v_add_u32_e32 v147, v210, v182
	v_lshlrev_b32_e32 v147, 3, v147
	s_nop 3
	global_load_dword v137, v147, s[38:39]
	global_load_dword v139, v147, s[38:39] offset:4
	global_load_dword v141, v147, s[38:39] offset:8
	global_load_dword v143, v147, s[38:39] offset:12
	s_or_b64 exec, exec, s[34:35]
	s_and_saveexec_b64 s[34:35], s[24:25]
	s_cbranch_execz .LBB0_609
	v_readlane_b32 s38, v252, 63
	v_lshl_add_u64 v[132:133], v[210:211], 0, v[176:177]
	v_readlane_b32 s39, v253, 0
	s_nop 1
	v_lshl_add_u64 v[132:133], v[132:133], 3, s[38:39]
	global_load_dwordx4 v[132:135], v[132:133], off
	s_waitcnt vmcnt(0)
	v_pk_mul_f32 v[222:223], v[214:215], v[132:133] op_sel:[1,1] op_sel_hi:[0,1]
	v_mul_f32_e32 v32, v219, v135
	v_pk_mul_f32 v[216:217], v[214:215], v[132:133] op_sel_hi:[1,0]
	v_pk_fma_f32 v[214:215], v[214:215], v[132:133], v[222:223] op_sel_hi:[1,0,1]
	v_pk_fma_f32 v[132:133], v[218:219], v[134:135], v[32:33] op_sel_hi:[1,1,0] neg_lo:[0,0,1] neg_hi:[0,0,1]
	v_mul_f32_e32 v32, v218, v135
	v_pk_fma_f32 v[134:135], v[218:219], v[134:135], v[32:33] op_sel:[1,0,0] op_sel_hi:[0,1,0]
	v_sub_f32_e32 v214, v216, v222
	v_mov_b32_e32 v218, v132
	v_mov_b32_e32 v219, v134
.LBB0_609:
	s_or_b64 exec, exec, s[34:35]
	v_pk_mul_f32 v[208:209], v[208:209], v[220:221]
	v_pk_mul_f32 v[206:207], v[212:213], v[206:207]
	s_and_saveexec_b64 s[34:35], s[26:27]
	s_cbranch_execz .LBB0_474
	s_waitcnt vmcnt(0)
	v_mov_b32_e32 v132, v137
	v_mov_b32_e32 v133, v139
	v_mov_b32_e32 v134, v141
	v_mov_b32_e32 v135, v143
	v_mov_b32_e32 v137, 0
	v_mov_b32_e32 v139, 0
	v_mov_b32_e32 v141, 0
	v_mov_b32_e32 v143, 0
	v_mov_b32_e32 v147, 0
	v_pk_mul_f32 v[212:213], v[206:207], v[132:133] op_sel:[1,1] op_sel_hi:[0,1]
	v_mul_f32_e32 v32, v209, v135
	v_pk_mul_f32 v[210:211], v[206:207], v[132:133] op_sel_hi:[1,0]
	v_pk_fma_f32 v[206:207], v[206:207], v[132:133], v[212:213] op_sel_hi:[1,0,1]
	v_pk_fma_f32 v[132:133], v[208:209], v[134:135], v[32:33] op_sel_hi:[1,1,0] neg_lo:[0,0,1] neg_hi:[0,0,1]
	v_mul_f32_e32 v32, v208, v135
	v_pk_fma_f32 v[134:135], v[208:209], v[134:135], v[32:33] op_sel:[1,0,0] op_sel_hi:[0,1,0]
	v_sub_f32_e32 v206, v210, v212
	v_mov_b32_e32 v208, v132
	v_mov_b32_e32 v209, v134
	s_branch .LBB0_474
